# m1 and m3 gate preambles: DPP row_shr/row_bcast scans + v_readlane instead of ds_bpermute hop chains
# baseline (speedup 1.0000x reference)
.LBB0_288:
	s_ashr_i32 s4, s26, 10
	s_and_b32 s28, s26, 0x7f
	s_ashr_i32 s5, s4, 31
	v_mov_b32_e32 v15, v194
	s_lshl_b64 s[20:21], s[4:5], 13
	s_lshl_b32 s4, s28, 6
	s_bfe_u32 s29, s26, 0x30007
	v_and_b32_e32 v14, 63, v15
	v_readfirstlane_b32 s27, v15
	s_or_b32 s20, s20, s4
	s_cmp_gt_u32 s27, 63
	v_cmp_gt_u32_e32 vcc, 16, v14
	s_cbranch_scc1 .LBB0_292
	v_or_b32_e32 v0, s20, v14
	v_mov_b32_e32 v1, s21
	v_lshlrev_b64 v[0:1], 6, v[0:1]
	v_lshl_add_u64 v[0:1], s[14:15], 0, v[0:1]
	s_lshl_b32 s86, s29, 2
	v_lshl_add_u64 v[0:1], v[0:1], 0, s[86:87]
	v_mov_b32_e32 v3, s86
	global_load_dword v2, v[0:1], off offset:32
	global_load_dword v4, v3, s[10:11]
	s_nop 0
	global_load_dword v0, v[0:1], off
	s_nop 0
	global_load_dword v1, v3, s[12:13]
	s_waitcnt vmcnt(2)
	v_add_f32_e32 v2, v2, v4
	s_waitcnt vmcnt(0)
	v_add_f32_e32 v0, v0, v1
	v_min_f32_e32 v1, 0, v2
	v_mul_f32_e64 v2, |v2|, s79
	v_exp_f32_e32 v4, v2
	s_nop 0
	v_add_f32_e32 v5, 1.0, v4
	v_add_f32_e32 v2, -1.0, v5
	v_sub_f32_e32 v3, v2, v5
	v_add_f32_e32 v3, 1.0, v3
	v_sub_f32_e32 v2, v4, v2
	v_add_f32_e32 v6, v2, v3
	v_frexp_mant_f32_e32 v2, v5
	v_cmp_gt_f32_e64 s[4:5], s85, v2
	v_cvt_f64_f32_e32 v[2:3], v5
	v_frexp_exp_i32_f64_e32 v2, v[2:3]
	v_subbrev_co_u32_e64 v2, s[4:5], 0, v2, s[4:5]
	v_sub_u32_e32 v3, 0, v2
	v_ldexp_f32 v5, v5, v3
	v_ldexp_f32 v3, v6, v3
	v_add_f32_e32 v6, -1.0, v5
	v_add_f32_e32 v7, 1.0, v6
	v_sub_f32_e32 v7, v5, v7
	v_add_f32_e32 v7, v3, v7
	v_add_f32_e32 v8, v6, v7
	v_sub_f32_e32 v6, v8, v6
	v_sub_f32_e32 v6, v7, v6
	v_add_f32_e32 v7, 1.0, v5
	v_add_f32_e32 v9, -1.0, v7
	v_sub_f32_e32 v5, v5, v9
	v_add_f32_e32 v3, v3, v5
	v_add_f32_e32 v5, v7, v3
	v_sub_f32_e32 v7, v5, v7
	v_sub_f32_e32 v3, v3, v7
	v_rcp_f32_e32 v7, v5
	v_cvt_f32_i32_e32 v2, v2
	s_mov_b32 s4, 0x3f317218
	v_mul_f32_e32 v9, v8, v7
	v_mul_f32_e32 v10, v5, v9
	v_fma_f32 v11, v9, v5, -v10
	v_fmac_f32_e32 v11, v9, v3
	v_add_f32_e32 v12, v10, v11
	v_sub_f32_e32 v13, v8, v12
	v_sub_f32_e32 v8, v8, v13
	v_sub_f32_e32 v10, v12, v10
	v_sub_f32_e32 v8, v8, v12
	v_add_f32_e32 v6, v6, v8
	v_sub_f32_e32 v8, v10, v11
	v_add_f32_e32 v6, v8, v6
	v_add_f32_e32 v8, v13, v6
	v_mul_f32_e32 v10, v7, v8
	v_mul_f32_e32 v11, v5, v10
	v_fma_f32 v5, v10, v5, -v11
	v_fmac_f32_e32 v5, v10, v3
	v_sub_f32_e32 v3, v13, v8
	v_add_f32_e32 v3, v6, v3
	v_add_f32_e32 v6, v11, v5
	v_sub_f32_e32 v12, v8, v6
	v_sub_f32_e32 v8, v8, v12
	v_sub_f32_e32 v11, v6, v11
	v_sub_f32_e32 v6, v8, v6
	v_add_f32_e32 v3, v3, v6
	v_sub_f32_e32 v5, v11, v5
	v_add_f32_e32 v3, v5, v3
	v_add_f32_e32 v5, v9, v10
	v_add_f32_e32 v3, v12, v3
	v_sub_f32_e32 v6, v5, v9
	v_mul_f32_e32 v3, v7, v3
	v_sub_f32_e32 v6, v10, v6
	v_add_f32_e32 v3, v6, v3
	v_mul_f32_e32 v9, 0x3f317218, v2
	v_add_f32_e32 v6, v5, v3
	v_fma_f32 v10, v2, s4, -v9
	v_mul_f32_e32 v7, v6, v6
	v_fmac_f32_e32 v10, 0xb102e308, v2
	v_sub_f32_e32 v2, v6, v5
	v_fmamk_f32 v8, v7, 0x3e9b6dac, v200
	v_sub_f32_e32 v2, v3, v2
	v_add_f32_e32 v3, v9, v10
	v_fmaak_f32 v8, v7, v8, 0x3f2aaada
	v_sub_f32_e32 v5, v3, v9
	v_ldexp_f32 v9, v6, 1
	v_mul_f32_e32 v6, v6, v7
	v_mul_f32_e32 v6, v6, v8
	v_add_f32_e32 v7, v9, v6
	v_sub_f32_e32 v8, v7, v9
	v_ldexp_f32 v2, v2, 1
	v_sub_f32_e32 v6, v6, v8
	v_add_f32_e32 v2, v2, v6
	v_add_f32_e32 v6, v7, v2
	v_sub_f32_e32 v7, v6, v7
	v_sub_f32_e32 v2, v2, v7
	v_add_f32_e32 v7, v3, v6
	v_sub_f32_e32 v8, v7, v3
	v_sub_f32_e32 v9, v7, v8
	v_sub_f32_e32 v5, v10, v5
	v_sub_f32_e32 v3, v3, v9
	v_sub_f32_e32 v6, v6, v8
	v_add_f32_e32 v3, v6, v3
	v_add_f32_e32 v6, v5, v2
	v_sub_f32_e32 v8, v6, v5
	v_sub_f32_e32 v9, v6, v8
	v_sub_f32_e32 v5, v5, v9
	v_sub_f32_e32 v2, v2, v8
	v_add_f32_e32 v3, v6, v3
	v_add_f32_e32 v2, v2, v5
	v_add_f32_e32 v5, v7, v3
	v_sub_f32_e32 v6, v5, v7
	v_sub_f32_e32 v3, v3, v6
	v_add_f32_e32 v2, v2, v3
	s_mov_b32 s4, 0x7f800000
	v_add_f32_e32 v2, v5, v2
	v_cmp_neq_f32_e64 s[4:5], s4, v4
	v_add_u32_e32 v3, -1, v201
	s_nop 0
	v_cndmask_b32_e64 v2, v202, v2, s[4:5]
	v_cmp_ngt_f32_e64 s[4:5], -1.0, v4
	s_nop 1
	v_cndmask_b32_e64 v2, v203, v2, s[4:5]
	v_cmp_neq_f32_e64 s[4:5], -1.0, v4
	s_nop 1
	v_cndmask_b32_e64 v2, v204, v2, s[4:5]
	s_mov_b32 s4, 0x33800000
	v_cmp_lt_f32_e64 s[4:5], |v4|, s4
	s_nop 1
	v_cndmask_b32_e64 v2, v2, v4, s[4:5]
	v_sub_f32_e32 v1, v1, v2
	v_mov_b32_e32 v4, v1
	s_nop 1
	v_add_f32_dpp v4, v1, v4 row_shr:1 row_mask:0xf bank_mask:0xf
	v_add_f32_dpp v4, v1, v4 row_shr:2 row_mask:0xf bank_mask:0xf
	v_add_f32_dpp v4, v1, v4 row_shr:3 row_mask:0xf bank_mask:0xf
	s_nop 1
	v_add_f32_dpp v4, v4, v4 row_shr:4 row_mask:0xf bank_mask:0xe
	s_nop 1
	v_add_f32_dpp v4, v4, v4 row_shr:8 row_mask:0xf bank_mask:0xc
	s_nop 1
	v_add_f32_dpp v4, v4, v4 row_bcast:15 row_mask:0xa bank_mask:0xf
	s_nop 1
	v_add_f32_dpp v4, v4, v4 row_bcast:31 row_mask:0xc bank_mask:0xf
	s_nop 0
	v_readlane_b32 s6, v4, 63
	s_nop 1
	v_mov_b32_e32 v1, s6
	v_sub_f32_e32 v2, v1, v4
	v_add_f32_e32 v2, v0, v2
	v_mov_b32_e32 v3, v2
	s_nop 1
	v_max_f32_dpp v3, v2, v3 row_shr:1 row_mask:0xf bank_mask:0xf
	v_max_f32_dpp v3, v2, v3 row_shr:2 row_mask:0xf bank_mask:0xf
	v_max_f32_dpp v3, v2, v3 row_shr:3 row_mask:0xf bank_mask:0xf
	s_nop 1
	v_max_f32_dpp v3, v3, v3 row_shr:4 row_mask:0xf bank_mask:0xe
	s_nop 1
	v_max_f32_dpp v3, v3, v3 row_shr:8 row_mask:0xf bank_mask:0xc
	s_nop 1
	v_max_f32_dpp v3, v3, v3 row_bcast:15 row_mask:0xa bank_mask:0xf
	s_nop 1
	v_max_f32_dpp v3, v3, v3 row_bcast:31 row_mask:0xc bank_mask:0xf
	s_nop 0
	v_readlane_b32 s7, v3, 63
	v_cmp_eq_u32_e64 s[4:5], 0, v14
	s_nop 1
	v_mov_b32_e32 v0, s7
	v_sub_f32_e32 v2, v2, v0
	v_mul_f32_e32 v2, 0x3fb8aa3b, v2
	v_exp_f32_e32 v2, v2
	v_lshl_add_u32 v3, v14, 2, 0
	ds_write_b32 v3, v2 offset:29952
	s_and_saveexec_b64 s[6:7], s[4:5]
	s_cbranch_execz .LBB0_291
	s_ashr_i32 s19, s18, 31
	s_lshl_b64 s[4:5], s[18:19], 2
	s_add_u32 s4, s24, s4
	s_addc_u32 s5, s25, s5
	global_store_dwordx2 v172, v[0:1], s[4:5]
